# attention items: score-bound words fetched once per workgroup into LDS instead of four system-scope loads per item
# baseline (speedup 1.0000x reference)
; #define LAS __attribute__((address_space(3)))
; __global__ void __launch_bounds__(NWAVES * 64, 2) fwd_megakernel(Args args) {
;     ...
;         unsigned* nmax = (unsigned*)(WSP(float, WS_SS) + 3 * S); unsigned* qctr = nmax + 64;
;         LAS unsigned* qw = (LAS unsigned*)(ldsp + 131072 + 512);
;         for (int rep_ = 0; rep_ < REP_P2; ++rep_) { bool first_ = true;
;         for (;;) {
;             if (threadIdx.x == 0) *qw = first_ ? (unsigned)bx : (unsigned)G + __hip_atomic_fetch_add(qctr + rep_, 1u, __ATOMIC_RELAXED, __HIP_MEMORY_SCOPE_AGENT);
;             first_ = false;
;             __syncthreads();
;             const unsigned pidx = __builtin_amdgcn_readfirstlane(*qw);
;             if (pidx >= 1152u) break;
;     ...
;             const float qa = __uint_as_float(__hip_atomic_load(nmax + hq * 2, __ATOMIC_RELAXED, __HIP_MEMORY_SCOPE_AGENT)), qc = __uint_as_float(__hip_atomic_load(nmax + hq * 2 + 1, __ATOMIC_RELAXED, __HIP_MEMORY_SCOPE_AGENT));
;             const float ka = __uint_as_float(__hip_atomic_load(nmax + (16 + hq) * 2, __ATOMIC_RELAXED, __HIP_MEMORY_SCOPE_AGENT)), kc = __uint_as_float(__hip_atomic_load(nmax + (16 + hq) * 2 + 1, __ATOMIC_RELAXED, __HIP_MEMORY_SCOPE_AGENT));
.LBB0_261:
	v_writelane_b32 v255, s74, 3
	s_ashr_i32 s83, s10, 6
	s_add_u32 s0, s12, 0xa400000
	v_writelane_b32 v255, s75, 4
	v_writelane_b32 v255, s0, 5
	s_addc_u32 s0, s13, 0
	v_writelane_b32 v255, s0, 6
	s_add_u32 s0, s12, 0xb400000
	v_writelane_b32 v255, s0, 7
	s_addc_u32 s0, s13, 0
	v_writelane_b32 v255, s0, 8
	s_add_u32 s0, s12, 0xc400000
	v_writelane_b32 v255, s0, 9
	s_addc_u32 s0, s13, 0
	v_writelane_b32 v255, s0, 10
	s_add_u32 s0, s12, 0x12400000
	s_addc_u32 s1, s13, 0
	v_writelane_b32 v255, s0, 11
	v_and_b32_e32 v2, 0x7f, v227
	v_lshlrev_b32_e32 v220, 4, v2
	v_writelane_b32 v255, s1, 12
	s_add_u32 s0, s12, 0x18000
	v_writelane_b32 v255, s0, 13
	s_addc_u32 s0, s13, 0
	s_add_u32 s18, s12, 0x18100
	s_addc_u32 s19, s13, 0
	s_add_u32 s20, s12, 0x7e00000
	s_addc_u32 s21, s13, 0
	s_add_u32 s22, s12, 0x6a00000
	s_addc_u32 s23, s13, 0
	s_add_u32 s24, s12, 0x6200000
	s_addc_u32 s25, s13, 0
	v_writelane_b32 v255, s0, 14
	s_movk_i32 s0, 0xff
	s_add_u32 s26, s12, 0x4200000
	v_cmp_lt_u32_e64 s[0:1], s0, v227
	s_addc_u32 s27, s13, 0
	v_mov_b32_e32 v221, 0
	v_writelane_b32 v255, s0, 15
	s_add_u32 s28, s12, 0x2200000
	v_lshl_add_u64 v[0:1], s[12:13], 0, v[220:221]
	v_writelane_b32 v255, s1, 16
	s_mov_b64 s[0:1], 0xd400000
	s_addc_u32 s29, s13, 0
	v_lshl_add_u64 v[222:223], v[0:1], 0, s[0:1]
	s_mov_b64 s[0:1], 0x8400800
	s_add_u32 s30, s12, 0x8000000
	v_lshl_add_u64 v[224:225], v[0:1], 0, s[0:1]
	s_addc_u32 s31, s13, 0
	s_lshl_b32 s0, s83, 5
	v_writelane_b32 v255, s0, 17
	s_add_i32 s4, 0, 0x20090
	v_writelane_b32 v255, s4, 18
	s_add_i32 s4, 0, 0x20098
	v_lshlrev_b32_e32 v0, 2, v140
	s_add_i32 s93, 0, 0x20200
	v_writelane_b32 v255, s4, 19
	s_add_i32 s4, 0, 0x20088
	v_or_b32_e32 v158, 0xfff40000, v227
	v_cmp_lt_u32_e64 s[6:7], 31, v2
	v_bfe_u32 v237, v227, 5, 2
	v_and_b32_e32 v226, 56, v140
	v_and_b32_e32 v228, 28, v0
	s_mov_b64 s[0:1], -1
	v_mov_b32_e32 v238, 1
	v_mov_b32_e32 v239, s93
	v_mov_b32_e32 v241, 0x260
	v_mov_b32_e32 v242, 0x42000000
	s_movk_i32 s95, 0x6000
	s_mov_b64 s[34:35], 0x80
	s_mov_b32 s96, 0x8000
	s_movk_i32 s97, 0x2000
	s_mov_b64 s[42:43], 0x40000
	s_movk_i32 s44, 0x4000
	s_mov_b32 s45, 0xa000
	s_mov_b32 s46, 0xc000
	s_mov_b64 s[48:49], 0xb480000
	s_mov_b64 s[50:51], 0xc440000
	s_mov_b64 s[52:53], 0xc440080
	s_mov_b64 s[54:55], 0xb4a0000
	s_mov_b64 s[58:59], 0xc460000
	s_mov_b64 s[60:61], 0xc460080
	s_mov_b32 s47, 0xffff0000
	s_movk_i32 s56, 0x7fff
	s_mov_b32 s81, 0xe000
	v_writelane_b32 v255, s4, 20
	s_movk_i32 s40, 0x1000
	s_add_i32 s41, 0, 0x20068
	s_add_i32 s37, 0, 0x20080
	s_add_i32 s82, 0, 0x20070
	s_add_i32 s84, 0, 0x20008
	v_mov_b32_e32 v243, 0x42800000
	v_mov_b32_e32 v244, 0xff800000
	v_readlane_b32 s64, v255, 13
	v_readlane_b32 s65, v255, 14
	v_and_b32_e32 v0, 63, v227
	v_lshlrev_b32_e32 v0, 2, v0
	v_add_u32_e32 v2, 0x20100, v0
	s_nop 4
	global_load_dword v1, v0, s[64:65] sc1
	s_waitcnt vmcnt(0)
	ds_write_b32 v2, v1
	s_waitcnt vmcnt(0) lgkmcnt(0)
	s_barrier
	s_branch .LBB0_265

; __global__ void __launch_bounds__(NWAVES * 64, 2) fwd_megakernel(Args args) {
;     ...
;             const float slope2 = __builtin_exp2f(-(float)(h_ + 1)) * 1.4426950408889634f;
;             const float qa = __uint_as_float(__hip_atomic_load(nmax + hq * 2, __ATOMIC_RELAXED, __HIP_MEMORY_SCOPE_AGENT)), qc = __uint_as_float(__hip_atomic_load(nmax + hq * 2 + 1, __ATOMIC_RELAXED, __HIP_MEMORY_SCOPE_AGENT));
;             const float ka = __uint_as_float(__hip_atomic_load(nmax + (16 + hq) * 2, __ATOMIC_RELAXED, __HIP_MEMORY_SCOPE_AGENT)), kc = __uint_as_float(__hip_atomic_load(nmax + (16 + hq) * 2 + 1, __ATOMIC_RELAXED, __HIP_MEMORY_SCOPE_AGENT));
;             const float bt = sqrtf((qa + qc) * (ka + kc)) * 1.02f + 0.01f;
;             const float dmin = fminf(ceilf((2.f * bt + 32.f - __builtin_log2f(1.f - __builtin_exp2f(-slope2))) / slope2), 1048576.f);
;             int t0 = (qb * 256 - (int)dmin + 1); t0 = t0 > 0 ? (t0 >> 6) & ~1 : 0;
;             t0 = __builtin_amdgcn_readfirstlane(t0);
;             const float bref = __uint_as_float(__builtin_amdgcn_readfirstlane(__float_as_uint(fminf(bt, 60.f))));
;             const int nt_all = 4 * qb + 4 - t0; const bool split = may_split && nt_all >= ATT_SPLIT_MIN; const int na = split ? (((nt_all >> 1) + 1) & ~1) : nt_all;
;             if (part == 1 && !split) { __syncthreads(); continue; }
.LBB0_276:
	s_lshl_b32 s0, s17, 3
	s_add_i32 s67, s64, s0
	s_add_i32 s0, s64, 1
	v_cvt_f32_u32_e32 v0, s0
	s_mov_b32 s5, 0x42fc0000
	s_sub_i32 s38, 31, s78
	v_readlane_b32 s4, v255, 13
	v_cmp_lt_f32_e32 vcc, s5, v0
	s_and_b64 s[0:1], vcc, exec
	s_cselect_b32 s0, 0xffffffc0, 0
	v_cndmask_b32_e32 v1, 0, v243, vcc
	v_sub_f32_e32 v0, v1, v0
	v_exp_f32_e32 v0, v0
	s_lshl_b32 s10, s67, 1
	v_ldexp_f32 v6, v0, s0
	s_lshl_b64 s[0:1], s[10:11], 2
	s_add_u32 s0, s4, s0
	v_readlane_b32 s4, v255, 14
	s_addc_u32 s1, s4, s1
	s_lshl_b32 s32, s10, 2
	s_add_i32 s32, s32, 0x20100
	v_mov_b32_e32 v0, s32
	ds_read_b32 v2, v0
	ds_read_b32 v4, v0 offset:4
	ds_read_b32 v3, v0 offset:128
	ds_read_b32 v5, v0 offset:132
	s_mov_b32 s0, 0xf800000
	v_mul_f32_e32 v245, 0x3fb8aa3b, v6
	s_waitcnt vmcnt(0) lgkmcnt(0)
	v_pk_add_f32 v[0:1], v[2:3], v[4:5]
	s_nop 0
	v_mul_f32_e32 v0, v0, v1
	v_cmp_gt_f32_e32 vcc, s0, v0
	v_mul_f32_e32 v1, 0x4f800000, v0
	s_nop 0
	v_cndmask_b32_e32 v0, v0, v1, vcc
	v_sqrt_f32_e32 v1, v0
	s_nop 0
	v_add_u32_e32 v2, -1, v1
	v_fma_f32 v3, -v2, v1, v0
	v_cmp_ge_f32_e64 s[0:1], 0, v3
	v_add_u32_e32 v3, 1, v1
	s_nop 0
	v_cndmask_b32_e64 v2, v1, v2, s[0:1]
	v_fma_f32 v1, -v3, v1, v0
	v_cmp_lt_f32_e64 s[0:1], 0, v1
	s_nop 1
	v_cndmask_b32_e64 v1, v2, v3, s[0:1]
	v_mul_f32_e32 v2, 0x37800000, v1
	v_cndmask_b32_e32 v1, v1, v2, vcc
	v_cmp_class_f32_e32 vcc, v0, v241
	s_nop 1
	v_cndmask_b32_e32 v0, v1, v0, vcc
	v_cmp_lt_f32_e32 vcc, s5, v245
	s_and_b64 s[0:1], vcc, exec
	s_cselect_b32 s0, 0xffffffc0, 0
	v_cndmask_b32_e32 v2, 0, v243, vcc
	v_fmac_f32_e32 v2, 0xbfb8aa3b, v6
	v_exp_f32_e32 v2, v2
	v_mov_b32_e32 v1, 0x3c23d70a
	v_fmamk_f32 v0, v0, 0x3f828f5c, v1
	v_fmaak_f32 v1, 2.0, v0, 0x42000000
	v_ldexp_f32 v2, v2, s0
	v_sub_f32_e32 v2, 1.0, v2
	s_mov_b32 s0, 0x800000
	v_cmp_gt_f32_e32 vcc, s0, v2
	s_and_b64 s[0:1], vcc, exec
	s_cselect_b32 s0, 32, 0
	v_ldexp_f32 v2, v2, s0
	v_log_f32_e32 v2, v2
	v_cndmask_b32_e32 v3, 0, v242, vcc
	s_lshl_b32 s4, s38, 8
	v_min_f32_e32 v0, 0x42700000, v0
	v_sub_f32_e32 v2, v2, v3
	v_sub_f32_e32 v1, v1, v2
	v_div_scale_f32 v2, s[0:1], v245, v245, v1
	v_rcp_f32_e32 v3, v2
	v_readfirstlane_b32 s5, v0
	v_fma_f32 v4, -v2, v3, 1.0
	v_fmac_f32_e32 v3, v4, v3
	v_div_scale_f32 v4, vcc, v1, v245, v1
	v_mul_f32_e32 v5, v4, v3
	v_fma_f32 v6, -v2, v5, v4
	v_fmac_f32_e32 v5, v6, v3
	v_fma_f32 v2, -v2, v5, v4
	v_div_fmas_f32 v2, v2, v3, v5
	v_div_fixup_f32 v1, v2, v245, v1
	v_ceil_f32_e32 v1, v1
	v_min_f32_e32 v1, 0x49800000, v1
	v_cvt_i32_f32_e32 v1, v1
	s_nop 0
	v_readfirstlane_b32 s0, v1
	s_sub_i32 s0, s4, s0
	s_add_i32 s1, s0, 1
	s_ashr_i32 s1, s1, 6
	s_and_b32 s1, s1, -2
	s_cmp_gt_i32 s0, -1
	s_cselect_b32 s66, s1, 0
	s_lshl_b32 s0, s38, 2
	s_sub_i32 s10, s0, s66
	s_add_i32 s10, s10, 4
	s_cmp_gt_i32 s10, 15
	s_cselect_b64 s[0:1], -1, 0
	s_and_b64 s[62:63], s[8:9], s[0:1]
	s_cmp_lg_u32 s16, 0
	s_cselect_b64 s[8:9], -1, 0
	s_cmp_eq_u32 s16, 0
	s_cselect_b64 s[38:39], -1, 0
	s_or_b64 s[38:39], s[38:39], s[62:63]
	s_mov_b64 s[0:1], -1
	s_and_b64 vcc, exec, s[38:39]
	s_cbranch_vccnz .LBB0_278
	s_mov_b64 s[0:1], 0
	s_barrier
